# rw_lora input stage: 12 bf16 loads per thread issued together, branch-free tanh select (on top of batched post1 g-gate stage)
# baseline (speedup 1.0000x reference)
.LBB0_944:
	s_lshl_b32 s18, s48, 4
	s_mov_b32 s10, 0xffffde00
	s_mov_b32 s11, -1
	s_mov_b32 s20, 0x2200
	s_mov_b32 s21, 0
	global_load_dword v50, v[2:3], off
	global_load_dword v51, v[4:5], off
	global_load_dword v52, v[6:7], off
	global_load_dword v53, v[8:9], off
	v_or_b32_e32 v20, s18, v220
	v_mad_i64_i32 v[22:23], s[0:1], v20, s23, v[14:15]
	v_lshl_add_u64 v[22:23], v[22:23], 0, s[16:17]
	v_lshl_add_u64 v[26:27], v[22:23], 0, v[0:1]
	v_lshl_add_u64 v[34:35], v[26:27], 0, s[10:11]
	v_lshl_add_u64 v[36:37], v[26:27], 0, s[20:21]
	global_load_ushort v38, v[26:27], off
	global_load_ushort v42, v[34:35], off
	global_load_ushort v46, v[36:37], off
	v_lshl_add_u64 v[28:29], v[22:23], 0, v[18:19]
	v_lshl_add_u64 v[34:35], v[28:29], 0, s[10:11]
	v_lshl_add_u64 v[36:37], v[28:29], 0, s[20:21]
	global_load_ushort v39, v[28:29], off
	global_load_ushort v43, v[34:35], off
	global_load_ushort v47, v[36:37], off
	v_or_b32_e32 v21, s18, v69
	v_mad_i64_i32 v[24:25], s[0:1], v21, s23, v[14:15]
	v_lshl_add_u64 v[24:25], v[24:25], 0, s[16:17]
	v_lshl_add_u64 v[30:31], v[24:25], 0, v[0:1]
	v_lshl_add_u64 v[34:35], v[30:31], 0, s[10:11]
	v_lshl_add_u64 v[36:37], v[30:31], 0, s[20:21]
	global_load_ushort v40, v[30:31], off
	global_load_ushort v44, v[34:35], off
	global_load_ushort v48, v[36:37], off
	v_lshl_add_u64 v[32:33], v[24:25], 0, v[18:19]
	v_lshl_add_u64 v[34:35], v[32:33], 0, s[10:11]
	v_lshl_add_u64 v[36:37], v[32:33], 0, s[20:21]
	global_load_ushort v41, v[32:33], off
	global_load_ushort v45, v[34:35], off
	global_load_ushort v49, v[36:37], off
	s_waitcnt vmcnt(0)
	v_and_b32_e32 v54, v71, v20
	v_lshlrev_b32_e32 v55, 16, v38
	v_lshlrev_b32_e32 v56, 16, v42
	v_lshlrev_b32_e32 v57, 16, v46
	v_cmp_ne_u32_e32 vcc, 0, v54
	s_nop 1
	v_cndmask_b32_e32 v56, 0, v56, vcc
	v_cmp_ne_u32_e32 vcc, s22, v54
	s_nop 1
	v_cndmask_b32_e32 v57, 0, v57, vcc
	v_sub_f32_e32 v56, v56, v55
	v_sub_f32_e32 v57, v57, v55
	v_mul_f32_e32 v56, v56, v50
	v_mul_f32_e32 v57, v57, v51
	v_add_f32_e32 v56, v56, v55
	v_add_f32_e32 v56, v56, v57
	v_add_f32_e64 v57, |v56|, |v56|
	v_mul_f32_e32 v58, 0x3fb8aa3b, v57
	v_rndne_f32_e32 v59, v58
	v_sub_f32_e32 v60, v58, v59
	v_fma_f32 v58, v57, s35, -v58
	v_fmac_f32_e32 v58, 0x32a5705f, v57
	v_add_f32_e32 v58, v60, v58
	v_cvt_i32_f32_e32 v59, v59
	v_exp_f32_e32 v58, v58
	v_cmp_ngt_f32_e32 vcc, s44, v57
	v_ldexp_f32 v58, v58, v59
	s_nop 0
	v_cndmask_b32_e32 v58, 0, v58, vcc
	v_cmp_nlt_f32_e32 vcc, s45, v57
	s_nop 1
	v_cndmask_b32_e32 v57, v73, v58, vcc
	v_add_f32_e32 v57, 1.0, v57
	v_rcp_f32_e32 v57, v57
	s_nop 0
	v_fma_f32 v58, v57, -2.0, 1.0
	v_mul_f32_e32 v57, v56, v56
	v_fmamk_f32 v59, v57, 0xbbbac73d, v72
	v_fmaak_f32 v59, v57, v59, 0xbd5c1c4e
	v_fmaak_f32 v59, v57, v59, 0x3e088382
	v_fmaak_f32 v59, v57, v59, 0xbeaaaa99
	v_mul_f32_e64 v59, |v56|, v59
	v_fma_f32 v59, v57, v59, |v56|
	v_cmp_nlt_f32_e64 vcc, |v56|, s34
	s_nop 1
	v_cndmask_b32_e32 v58, v59, v58, vcc
	v_bfi_b32 v56, s46, v58, v56
	ds_write_b32 v68, v56
	v_and_b32_e32 v54, v71, v20
	v_lshlrev_b32_e32 v55, 16, v39
	v_lshlrev_b32_e32 v56, 16, v43
	v_lshlrev_b32_e32 v57, 16, v47
	v_cmp_ne_u32_e32 vcc, 0, v54
	s_nop 1
	v_cndmask_b32_e32 v56, 0, v56, vcc
	v_cmp_ne_u32_e32 vcc, s22, v54
	s_nop 1
	v_cndmask_b32_e32 v57, 0, v57, vcc
	v_sub_f32_e32 v56, v56, v55
	v_sub_f32_e32 v57, v57, v55
	v_mul_f32_e32 v56, v56, v52
	v_mul_f32_e32 v57, v57, v53
	v_add_f32_e32 v56, v56, v55
	v_add_f32_e32 v56, v56, v57
	ds_write_b32 v68, v56 offset:4096
	v_and_b32_e32 v54, v71, v21
	v_lshlrev_b32_e32 v55, 16, v40
	v_lshlrev_b32_e32 v56, 16, v44
	v_lshlrev_b32_e32 v57, 16, v48
	v_cmp_ne_u32_e32 vcc, 0, v54
	s_nop 1
	v_cndmask_b32_e32 v56, 0, v56, vcc
	v_cmp_ne_u32_e32 vcc, s22, v54
	s_nop 1
	v_cndmask_b32_e32 v57, 0, v57, vcc
	v_sub_f32_e32 v56, v56, v55
	v_sub_f32_e32 v57, v57, v55
	v_mul_f32_e32 v56, v56, v50
	v_mul_f32_e32 v57, v57, v51
	v_add_f32_e32 v56, v56, v55
	v_add_f32_e32 v56, v56, v57
	v_add_f32_e64 v57, |v56|, |v56|
	v_mul_f32_e32 v58, 0x3fb8aa3b, v57
	v_rndne_f32_e32 v59, v58
	v_sub_f32_e32 v60, v58, v59
	v_fma_f32 v58, v57, s35, -v58
	v_fmac_f32_e32 v58, 0x32a5705f, v57
	v_add_f32_e32 v58, v60, v58
	v_cvt_i32_f32_e32 v59, v59
	v_exp_f32_e32 v58, v58
	v_cmp_ngt_f32_e32 vcc, s44, v57
	v_ldexp_f32 v58, v58, v59
	s_nop 0
	v_cndmask_b32_e32 v58, 0, v58, vcc
	v_cmp_nlt_f32_e32 vcc, s45, v57
	s_nop 1
	v_cndmask_b32_e32 v57, v73, v58, vcc
	v_add_f32_e32 v57, 1.0, v57
	v_rcp_f32_e32 v57, v57
	s_nop 0
	v_fma_f32 v58, v57, -2.0, 1.0
	v_mul_f32_e32 v57, v56, v56
	v_fmamk_f32 v59, v57, 0xbbbac73d, v72
	v_fmaak_f32 v59, v57, v59, 0xbd5c1c4e
	v_fmaak_f32 v59, v57, v59, 0x3e088382
	v_fmaak_f32 v59, v57, v59, 0xbeaaaa99
	v_mul_f32_e64 v59, |v56|, v59
	v_fma_f32 v59, v57, v59, |v56|
	v_cmp_nlt_f32_e64 vcc, |v56|, s34
	s_nop 1
	v_cndmask_b32_e32 v58, v59, v58, vcc
	v_bfi_b32 v56, s46, v58, v56
	ds_write_b32 v70, v56
	v_and_b32_e32 v54, v71, v21
	v_lshlrev_b32_e32 v55, 16, v41
	v_lshlrev_b32_e32 v56, 16, v45
	v_lshlrev_b32_e32 v57, 16, v49
	v_cmp_ne_u32_e32 vcc, 0, v54
	s_nop 1
	v_cndmask_b32_e32 v56, 0, v56, vcc
	v_cmp_ne_u32_e32 vcc, s22, v54
	s_nop 1
	v_cndmask_b32_e32 v57, 0, v57, vcc
	v_sub_f32_e32 v56, v56, v55
	v_sub_f32_e32 v57, v57, v55
	v_mul_f32_e32 v56, v56, v52
	v_mul_f32_e32 v57, v57, v53
	v_add_f32_e32 v56, v56, v55
	v_add_f32_e32 v56, v56, v57
	ds_write_b32 v70, v56 offset:4096
	s_waitcnt lgkmcnt(0)
	s_barrier
	v_and_b32_e32 v112, 63, v164
	v_lshrrev_b32_e32 v113, 6, v164
	v_lshlrev_b32_e32 v107, 2, v112
	v_lshrrev_b32_e32 v114, 4, v112
	v_and_b32_e32 v115, 15, v112
	v_lshlrev_b32_e32 v111, 11, v114
	v_lshl_add_u32 v111, v113, 8, v111
	v_lshl_add_u32 v111, v115, 4, v111
	v_mul_u32_u24_e32 v110, 0x3000, v113
	v_add_u32_e32 v110, 0x2000, v110
	v_lshl_add_u32 v109, v114, 10, v110
	v_lshl_add_u32 v109, v115, 4, v109
	v_lshl_add_u32 v110, v112, 2, v110
	v_readlane_b32 s0, v255, 27
	v_readlane_b32 s1, v255, 28
	v_mov_b32_e32 v108, v111
	v_mov_b32_e32 v76, 0
	v_mov_b32_e32 v77, 0
	v_mov_b32_e32 v78, 0
	v_mov_b32_e32 v79, 0
	v_mov_b32_e32 v80, 0
	v_mov_b32_e32 v81, 0
	v_mov_b32_e32 v82, 0
	v_mov_b32_e32 v83, 0
	v_mov_b32_e32 v84, 0
	v_mov_b32_e32 v85, 0
	v_mov_b32_e32 v86, 0
	v_mov_b32_e32 v87, 0
	v_mov_b32_e32 v88, 0
	v_mov_b32_e32 v89, 0
	v_mov_b32_e32 v90, 0
	v_mov_b32_e32 v91, 0
	global_load_dwordx4 v[92:95], v108, s[0:1]
	v_add_u32_e32 v108, 0x2000, v108
	ds_read_b32 v104, v107 offset:0
	global_load_dwordx4 v[96:99], v108, s[0:1]
	v_add_u32_e32 v108, 0x2000, v108
	ds_read_b32 v105, v107 offset:256
	global_load_dwordx4 v[100:103], v108, s[0:1]
	v_add_u32_e32 v108, 0x2000, v108
	ds_read_b32 v106, v107 offset:512
	s_waitcnt vmcnt(2) lgkmcnt(2)
	v_mfma_f32_16x16x4_f32 v[76:79], v104, v92, v[76:79]
	v_mfma_f32_16x16x4_f32 v[80:83], v104, v93, v[80:83]
	v_mfma_f32_16x16x4_f32 v[84:87], v104, v94, v[84:87]
	v_mfma_f32_16x16x4_f32 v[88:91], v104, v95, v[88:91]
	global_load_dwordx4 v[92:95], v108, s[0:1]
	v_add_u32_e32 v108, 0x2000, v108
	ds_read_b32 v104, v107 offset:768
	s_waitcnt vmcnt(2) lgkmcnt(2)
	v_mfma_f32_16x16x4_f32 v[76:79], v105, v96, v[76:79]
	v_mfma_f32_16x16x4_f32 v[80:83], v105, v97, v[80:83]
	v_mfma_f32_16x16x4_f32 v[84:87], v105, v98, v[84:87]
	v_mfma_f32_16x16x4_f32 v[88:91], v105, v99, v[88:91]
	global_load_dwordx4 v[96:99], v108, s[0:1]
	v_add_u32_e32 v108, 0x2000, v108
	ds_read_b32 v105, v107 offset:1024
	s_waitcnt vmcnt(2) lgkmcnt(2)
	v_mfma_f32_16x16x4_f32 v[76:79], v106, v100, v[76:79]
	v_mfma_f32_16x16x4_f32 v[80:83], v106, v101, v[80:83]
	v_mfma_f32_16x16x4_f32 v[84:87], v106, v102, v[84:87]
	v_mfma_f32_16x16x4_f32 v[88:91], v106, v103, v[88:91]
	global_load_dwordx4 v[100:103], v108, s[0:1]
	v_add_u32_e32 v108, 0x2000, v108
	ds_read_b32 v106, v107 offset:1280
	s_waitcnt vmcnt(2) lgkmcnt(2)
	v_mfma_f32_16x16x4_f32 v[76:79], v104, v92, v[76:79]
	v_mfma_f32_16x16x4_f32 v[80:83], v104, v93, v[80:83]
	v_mfma_f32_16x16x4_f32 v[84:87], v104, v94, v[84:87]
	v_mfma_f32_16x16x4_f32 v[88:91], v104, v95, v[88:91]
	global_load_dwordx4 v[92:95], v108, s[0:1]
	v_add_u32_e32 v108, 0x2000, v108
	ds_read_b32 v104, v107 offset:1536
	s_waitcnt vmcnt(2) lgkmcnt(2)
	v_mfma_f32_16x16x4_f32 v[76:79], v105, v96, v[76:79]
	v_mfma_f32_16x16x4_f32 v[80:83], v105, v97, v[80:83]
	v_mfma_f32_16x16x4_f32 v[84:87], v105, v98, v[84:87]
	v_mfma_f32_16x16x4_f32 v[88:91], v105, v99, v[88:91]
	global_load_dwordx4 v[96:99], v108, s[0:1]
	v_add_u32_e32 v108, 0x2000, v108
	ds_read_b32 v105, v107 offset:1792
	s_waitcnt vmcnt(2) lgkmcnt(2)
	v_mfma_f32_16x16x4_f32 v[76:79], v106, v100, v[76:79]
	v_mfma_f32_16x16x4_f32 v[80:83], v106, v101, v[80:83]
	v_mfma_f32_16x16x4_f32 v[84:87], v106, v102, v[84:87]
	v_mfma_f32_16x16x4_f32 v[88:91], v106, v103, v[88:91]
	global_load_dwordx4 v[100:103], v108, s[0:1]
	v_add_u32_e32 v108, 0x2000, v108
	ds_read_b32 v106, v107 offset:2048
	s_waitcnt vmcnt(2) lgkmcnt(2)
	v_mfma_f32_16x16x4_f32 v[76:79], v104, v92, v[76:79]
	v_mfma_f32_16x16x4_f32 v[80:83], v104, v93, v[80:83]
	v_mfma_f32_16x16x4_f32 v[84:87], v104, v94, v[84:87]
	v_mfma_f32_16x16x4_f32 v[88:91], v104, v95, v[88:91]
	global_load_dwordx4 v[92:95], v108, s[0:1]
	v_add_u32_e32 v108, 0x2000, v108
	ds_read_b32 v104, v107 offset:2304
	s_waitcnt vmcnt(2) lgkmcnt(2)
	v_mfma_f32_16x16x4_f32 v[76:79], v105, v96, v[76:79]
	v_mfma_f32_16x16x4_f32 v[80:83], v105, v97, v[80:83]
	v_mfma_f32_16x16x4_f32 v[84:87], v105, v98, v[84:87]
	v_mfma_f32_16x16x4_f32 v[88:91], v105, v99, v[88:91]
	global_load_dwordx4 v[96:99], v108, s[0:1]
	v_add_u32_e32 v108, 0x2000, v108
	ds_read_b32 v105, v107 offset:2560
	s_waitcnt vmcnt(2) lgkmcnt(2)
	v_mfma_f32_16x16x4_f32 v[76:79], v106, v100, v[76:79]
	v_mfma_f32_16x16x4_f32 v[80:83], v106, v101, v[80:83]
	v_mfma_f32_16x16x4_f32 v[84:87], v106, v102, v[84:87]
	v_mfma_f32_16x16x4_f32 v[88:91], v106, v103, v[88:91]
	global_load_dwordx4 v[100:103], v108, s[0:1]
	v_add_u32_e32 v108, 0x2000, v108
	ds_read_b32 v106, v107 offset:2816
	s_waitcnt vmcnt(2) lgkmcnt(2)
	v_mfma_f32_16x16x4_f32 v[76:79], v104, v92, v[76:79]
	v_mfma_f32_16x16x4_f32 v[80:83], v104, v93, v[80:83]
	v_mfma_f32_16x16x4_f32 v[84:87], v104, v94, v[84:87]
	v_mfma_f32_16x16x4_f32 v[88:91], v104, v95, v[88:91]
	global_load_dwordx4 v[92:95], v108, s[0:1]
	v_add_u32_e32 v108, 0x2000, v108
	ds_read_b32 v104, v107 offset:3072
	s_waitcnt vmcnt(2) lgkmcnt(2)
	v_mfma_f32_16x16x4_f32 v[76:79], v105, v96, v[76:79]
	v_mfma_f32_16x16x4_f32 v[80:83], v105, v97, v[80:83]
	v_mfma_f32_16x16x4_f32 v[84:87], v105, v98, v[84:87]
	v_mfma_f32_16x16x4_f32 v[88:91], v105, v99, v[88:91]
	global_load_dwordx4 v[96:99], v108, s[0:1]
	v_add_u32_e32 v108, 0x2000, v108
	ds_read_b32 v105, v107 offset:3328
	s_waitcnt vmcnt(2) lgkmcnt(2)
	v_mfma_f32_16x16x4_f32 v[76:79], v106, v100, v[76:79]
	v_mfma_f32_16x16x4_f32 v[80:83], v106, v101, v[80:83]
	v_mfma_f32_16x16x4_f32 v[84:87], v106, v102, v[84:87]
	v_mfma_f32_16x16x4_f32 v[88:91], v106, v103, v[88:91]
	global_load_dwordx4 v[100:103], v108, s[0:1]
	v_add_u32_e32 v108, 0x2000, v108
	ds_read_b32 v106, v107 offset:3584
	s_waitcnt vmcnt(2) lgkmcnt(2)
	v_mfma_f32_16x16x4_f32 v[76:79], v104, v92, v[76:79]
	v_mfma_f32_16x16x4_f32 v[80:83], v104, v93, v[80:83]
	v_mfma_f32_16x16x4_f32 v[84:87], v104, v94, v[84:87]
	v_mfma_f32_16x16x4_f32 v[88:91], v104, v95, v[88:91]
	global_load_dwordx4 v[92:95], v108, s[0:1]
	v_add_u32_e32 v108, 0x2000, v108
	ds_read_b32 v104, v107 offset:3840
	s_waitcnt vmcnt(2) lgkmcnt(2)
	v_mfma_f32_16x16x4_f32 v[76:79], v105, v96, v[76:79]
	v_mfma_f32_16x16x4_f32 v[80:83], v105, v97, v[80:83]
	v_mfma_f32_16x16x4_f32 v[84:87], v105, v98, v[84:87]
	v_mfma_f32_16x16x4_f32 v[88:91], v105, v99, v[88:91]
	s_waitcnt vmcnt(1) lgkmcnt(1)
	v_mfma_f32_16x16x4_f32 v[76:79], v106, v100, v[76:79]
	v_mfma_f32_16x16x4_f32 v[80:83], v106, v101, v[80:83]
	v_mfma_f32_16x16x4_f32 v[84:87], v106, v102, v[84:87]
	v_mfma_f32_16x16x4_f32 v[88:91], v106, v103, v[88:91]
	s_waitcnt vmcnt(0) lgkmcnt(0)
	v_mfma_f32_16x16x4_f32 v[76:79], v104, v92, v[76:79]
	v_mfma_f32_16x16x4_f32 v[80:83], v104, v93, v[80:83]
	v_mfma_f32_16x16x4_f32 v[84:87], v104, v94, v[84:87]
	v_mfma_f32_16x16x4_f32 v[88:91], v104, v95, v[88:91]
	s_nop 15
	s_nop 3
	ds_write_b32 v109, v76 offset:0
	ds_write_b32 v109, v77 offset:256
	ds_write_b32 v109, v78 offset:512
	ds_write_b32 v109, v79 offset:768
	ds_write_b32 v109, v80 offset:4
	ds_write_b32 v109, v81 offset:260
	ds_write_b32 v109, v82 offset:516
	ds_write_b32 v109, v83 offset:772
	ds_write_b32 v109, v84 offset:8
	ds_write_b32 v109, v85 offset:264
	ds_write_b32 v109, v86 offset:520
	ds_write_b32 v109, v87 offset:776
	ds_write_b32 v109, v88 offset:12
	ds_write_b32 v109, v89 offset:268
	ds_write_b32 v109, v90 offset:524
	ds_write_b32 v109, v91 offset:780
	s_waitcnt lgkmcnt(0)
	s_add_u32 s0, s0, 0x20000
	s_addc_u32 s1, s1, 0
	v_mov_b32_e32 v108, v111
	v_mov_b32_e32 v76, 0
	v_mov_b32_e32 v77, 0
	v_mov_b32_e32 v78, 0
	v_mov_b32_e32 v79, 0
	v_mov_b32_e32 v80, 0
	v_mov_b32_e32 v81, 0
	v_mov_b32_e32 v82, 0
	v_mov_b32_e32 v83, 0
	v_mov_b32_e32 v84, 0
	v_mov_b32_e32 v85, 0
	v_mov_b32_e32 v86, 0
	v_mov_b32_e32 v87, 0
	v_mov_b32_e32 v88, 0
	v_mov_b32_e32 v89, 0
	v_mov_b32_e32 v90, 0
	v_mov_b32_e32 v91, 0
	global_load_dwordx4 v[92:95], v108, s[0:1]
	v_add_u32_e32 v108, 0x2000, v108
	ds_read_b32 v104, v107 offset:0
	global_load_dwordx4 v[96:99], v108, s[0:1]
	v_add_u32_e32 v108, 0x2000, v108
	ds_read_b32 v105, v107 offset:256
	global_load_dwordx4 v[100:103], v108, s[0:1]
	v_add_u32_e32 v108, 0x2000, v108
	ds_read_b32 v106, v107 offset:512
	s_waitcnt vmcnt(2) lgkmcnt(2)
	v_mfma_f32_16x16x4_f32 v[76:79], v104, v92, v[76:79]
	v_mfma_f32_16x16x4_f32 v[80:83], v104, v93, v[80:83]
	v_mfma_f32_16x16x4_f32 v[84:87], v104, v94, v[84:87]
	v_mfma_f32_16x16x4_f32 v[88:91], v104, v95, v[88:91]
	global_load_dwordx4 v[92:95], v108, s[0:1]
	v_add_u32_e32 v108, 0x2000, v108
	ds_read_b32 v104, v107 offset:768
	s_waitcnt vmcnt(2) lgkmcnt(2)
	v_mfma_f32_16x16x4_f32 v[76:79], v105, v96, v[76:79]
	v_mfma_f32_16x16x4_f32 v[80:83], v105, v97, v[80:83]
	v_mfma_f32_16x16x4_f32 v[84:87], v105, v98, v[84:87]
	v_mfma_f32_16x16x4_f32 v[88:91], v105, v99, v[88:91]
	global_load_dwordx4 v[96:99], v108, s[0:1]
	v_add_u32_e32 v108, 0x2000, v108
	ds_read_b32 v105, v107 offset:1024
	s_waitcnt vmcnt(2) lgkmcnt(2)
	v_mfma_f32_16x16x4_f32 v[76:79], v106, v100, v[76:79]
	v_mfma_f32_16x16x4_f32 v[80:83], v106, v101, v[80:83]
	v_mfma_f32_16x16x4_f32 v[84:87], v106, v102, v[84:87]
	v_mfma_f32_16x16x4_f32 v[88:91], v106, v103, v[88:91]
	global_load_dwordx4 v[100:103], v108, s[0:1]
	v_add_u32_e32 v108, 0x2000, v108
	ds_read_b32 v106, v107 offset:1280
	s_waitcnt vmcnt(2) lgkmcnt(2)
	v_mfma_f32_16x16x4_f32 v[76:79], v104, v92, v[76:79]
	v_mfma_f32_16x16x4_f32 v[80:83], v104, v93, v[80:83]
	v_mfma_f32_16x16x4_f32 v[84:87], v104, v94, v[84:87]
	v_mfma_f32_16x16x4_f32 v[88:91], v104, v95, v[88:91]
	global_load_dwordx4 v[92:95], v108, s[0:1]
	v_add_u32_e32 v108, 0x2000, v108
	ds_read_b32 v104, v107 offset:1536
	s_waitcnt vmcnt(2) lgkmcnt(2)
	v_mfma_f32_16x16x4_f32 v[76:79], v105, v96, v[76:79]
	v_mfma_f32_16x16x4_f32 v[80:83], v105, v97, v[80:83]
	v_mfma_f32_16x16x4_f32 v[84:87], v105, v98, v[84:87]
	v_mfma_f32_16x16x4_f32 v[88:91], v105, v99, v[88:91]
	global_load_dwordx4 v[96:99], v108, s[0:1]
	v_add_u32_e32 v108, 0x2000, v108
	ds_read_b32 v105, v107 offset:1792
	s_waitcnt vmcnt(2) lgkmcnt(2)
	v_mfma_f32_16x16x4_f32 v[76:79], v106, v100, v[76:79]
	v_mfma_f32_16x16x4_f32 v[80:83], v106, v101, v[80:83]
	v_mfma_f32_16x16x4_f32 v[84:87], v106, v102, v[84:87]
	v_mfma_f32_16x16x4_f32 v[88:91], v106, v103, v[88:91]
	global_load_dwordx4 v[100:103], v108, s[0:1]
	v_add_u32_e32 v108, 0x2000, v108
	ds_read_b32 v106, v107 offset:2048
	s_waitcnt vmcnt(2) lgkmcnt(2)
	v_mfma_f32_16x16x4_f32 v[76:79], v104, v92, v[76:79]
	v_mfma_f32_16x16x4_f32 v[80:83], v104, v93, v[80:83]
	v_mfma_f32_16x16x4_f32 v[84:87], v104, v94, v[84:87]
	v_mfma_f32_16x16x4_f32 v[88:91], v104, v95, v[88:91]
	global_load_dwordx4 v[92:95], v108, s[0:1]
	v_add_u32_e32 v108, 0x2000, v108
	ds_read_b32 v104, v107 offset:2304
	s_waitcnt vmcnt(2) lgkmcnt(2)
	v_mfma_f32_16x16x4_f32 v[76:79], v105, v96, v[76:79]
	v_mfma_f32_16x16x4_f32 v[80:83], v105, v97, v[80:83]
	v_mfma_f32_16x16x4_f32 v[84:87], v105, v98, v[84:87]
	v_mfma_f32_16x16x4_f32 v[88:91], v105, v99, v[88:91]
	global_load_dwordx4 v[96:99], v108, s[0:1]
	v_add_u32_e32 v108, 0x2000, v108
	ds_read_b32 v105, v107 offset:2560
	s_waitcnt vmcnt(2) lgkmcnt(2)
	v_mfma_f32_16x16x4_f32 v[76:79], v106, v100, v[76:79]
	v_mfma_f32_16x16x4_f32 v[80:83], v106, v101, v[80:83]
	v_mfma_f32_16x16x4_f32 v[84:87], v106, v102, v[84:87]
	v_mfma_f32_16x16x4_f32 v[88:91], v106, v103, v[88:91]
	global_load_dwordx4 v[100:103], v108, s[0:1]
	v_add_u32_e32 v108, 0x2000, v108
	ds_read_b32 v106, v107 offset:2816
	s_waitcnt vmcnt(2) lgkmcnt(2)
	v_mfma_f32_16x16x4_f32 v[76:79], v104, v92, v[76:79]
	v_mfma_f32_16x16x4_f32 v[80:83], v104, v93, v[80:83]
	v_mfma_f32_16x16x4_f32 v[84:87], v104, v94, v[84:87]
	v_mfma_f32_16x16x4_f32 v[88:91], v104, v95, v[88:91]
	global_load_dwordx4 v[92:95], v108, s[0:1]
	v_add_u32_e32 v108, 0x2000, v108
	ds_read_b32 v104, v107 offset:3072
	s_waitcnt vmcnt(2) lgkmcnt(2)
	v_mfma_f32_16x16x4_f32 v[76:79], v105, v96, v[76:79]
	v_mfma_f32_16x16x4_f32 v[80:83], v105, v97, v[80:83]
	v_mfma_f32_16x16x4_f32 v[84:87], v105, v98, v[84:87]
	v_mfma_f32_16x16x4_f32 v[88:91], v105, v99, v[88:91]
	global_load_dwordx4 v[96:99], v108, s[0:1]
	v_add_u32_e32 v108, 0x2000, v108
	ds_read_b32 v105, v107 offset:3328
	s_waitcnt vmcnt(2) lgkmcnt(2)
	v_mfma_f32_16x16x4_f32 v[76:79], v106, v100, v[76:79]
	v_mfma_f32_16x16x4_f32 v[80:83], v106, v101, v[80:83]
	v_mfma_f32_16x16x4_f32 v[84:87], v106, v102, v[84:87]
	v_mfma_f32_16x16x4_f32 v[88:91], v106, v103, v[88:91]
	global_load_dwordx4 v[100:103], v108, s[0:1]
	v_add_u32_e32 v108, 0x2000, v108
	ds_read_b32 v106, v107 offset:3584
	s_waitcnt vmcnt(2) lgkmcnt(2)
	v_mfma_f32_16x16x4_f32 v[76:79], v104, v92, v[76:79]
	v_mfma_f32_16x16x4_f32 v[80:83], v104, v93, v[80:83]
	v_mfma_f32_16x16x4_f32 v[84:87], v104, v94, v[84:87]
	v_mfma_f32_16x16x4_f32 v[88:91], v104, v95, v[88:91]
	global_load_dwordx4 v[92:95], v108, s[0:1]
	v_add_u32_e32 v108, 0x2000, v108
	ds_read_b32 v104, v107 offset:3840
	s_waitcnt vmcnt(2) lgkmcnt(2)
	v_mfma_f32_16x16x4_f32 v[76:79], v105, v96, v[76:79]
	v_mfma_f32_16x16x4_f32 v[80:83], v105, v97, v[80:83]
	v_mfma_f32_16x16x4_f32 v[84:87], v105, v98, v[84:87]
	v_mfma_f32_16x16x4_f32 v[88:91], v105, v99, v[88:91]
	s_waitcnt vmcnt(1) lgkmcnt(1)
	v_mfma_f32_16x16x4_f32 v[76:79], v106, v100, v[76:79]
	v_mfma_f32_16x16x4_f32 v[80:83], v106, v101, v[80:83]
	v_mfma_f32_16x16x4_f32 v[84:87], v106, v102, v[84:87]
	v_mfma_f32_16x16x4_f32 v[88:91], v106, v103, v[88:91]
	s_waitcnt vmcnt(0) lgkmcnt(0)
	v_mfma_f32_16x16x4_f32 v[76:79], v104, v92, v[76:79]
	v_mfma_f32_16x16x4_f32 v[80:83], v104, v93, v[80:83]
	v_mfma_f32_16x16x4_f32 v[84:87], v104, v94, v[84:87]
	v_mfma_f32_16x16x4_f32 v[88:91], v104, v95, v[88:91]
	s_nop 15
	s_nop 3
	ds_write_b32 v109, v76 offset:4096
	ds_write_b32 v109, v77 offset:4352
	ds_write_b32 v109, v78 offset:4608
	ds_write_b32 v109, v79 offset:4864
	ds_write_b32 v109, v80 offset:4100
	ds_write_b32 v109, v81 offset:4356
	ds_write_b32 v109, v82 offset:4612
	ds_write_b32 v109, v83 offset:4868
	ds_write_b32 v109, v84 offset:4104
	ds_write_b32 v109, v85 offset:4360
	ds_write_b32 v109, v86 offset:4616
	ds_write_b32 v109, v87 offset:4872
	ds_write_b32 v109, v88 offset:4108
	ds_write_b32 v109, v89 offset:4364
	ds_write_b32 v109, v90 offset:4620
	ds_write_b32 v109, v91 offset:4876
	s_waitcnt lgkmcnt(0)
	v_readlane_b32 s0, v255, 31
	v_readlane_b32 s1, v255, 32
	v_mov_b32_e32 v108, v111
	v_mov_b32_e32 v76, 0
	v_mov_b32_e32 v77, 0
	v_mov_b32_e32 v78, 0
	v_mov_b32_e32 v79, 0
	v_mov_b32_e32 v80, 0
	v_mov_b32_e32 v81, 0
	v_mov_b32_e32 v82, 0
	v_mov_b32_e32 v83, 0
	v_mov_b32_e32 v84, 0
	v_mov_b32_e32 v85, 0
	v_mov_b32_e32 v86, 0
	v_mov_b32_e32 v87, 0
	v_mov_b32_e32 v88, 0
	v_mov_b32_e32 v89, 0
	v_mov_b32_e32 v90, 0
	v_mov_b32_e32 v91, 0
	global_load_dwordx4 v[92:95], v108, s[0:1]
	v_add_u32_e32 v108, 0x2000, v108
	ds_read_b32 v104, v107 offset:4096
	global_load_dwordx4 v[96:99], v108, s[0:1]
	v_add_u32_e32 v108, 0x2000, v108
	ds_read_b32 v105, v107 offset:4352
	global_load_dwordx4 v[100:103], v108, s[0:1]
	v_add_u32_e32 v108, 0x2000, v108
	ds_read_b32 v106, v107 offset:4608
	s_waitcnt vmcnt(2) lgkmcnt(2)
	v_mfma_f32_16x16x4_f32 v[76:79], v104, v92, v[76:79]
	v_mfma_f32_16x16x4_f32 v[80:83], v104, v93, v[80:83]
	v_mfma_f32_16x16x4_f32 v[84:87], v104, v94, v[84:87]
	v_mfma_f32_16x16x4_f32 v[88:91], v104, v95, v[88:91]
	global_load_dwordx4 v[92:95], v108, s[0:1]
	v_add_u32_e32 v108, 0x2000, v108
	ds_read_b32 v104, v107 offset:4864
	s_waitcnt vmcnt(2) lgkmcnt(2)
	v_mfma_f32_16x16x4_f32 v[76:79], v105, v96, v[76:79]
	v_mfma_f32_16x16x4_f32 v[80:83], v105, v97, v[80:83]
	v_mfma_f32_16x16x4_f32 v[84:87], v105, v98, v[84:87]
	v_mfma_f32_16x16x4_f32 v[88:91], v105, v99, v[88:91]
	global_load_dwordx4 v[96:99], v108, s[0:1]
	v_add_u32_e32 v108, 0x2000, v108
	ds_read_b32 v105, v107 offset:5120
	s_waitcnt vmcnt(2) lgkmcnt(2)
	v_mfma_f32_16x16x4_f32 v[76:79], v106, v100, v[76:79]
	v_mfma_f32_16x16x4_f32 v[80:83], v106, v101, v[80:83]
	v_mfma_f32_16x16x4_f32 v[84:87], v106, v102, v[84:87]
	v_mfma_f32_16x16x4_f32 v[88:91], v106, v103, v[88:91]
	global_load_dwordx4 v[100:103], v108, s[0:1]
	v_add_u32_e32 v108, 0x2000, v108
	ds_read_b32 v106, v107 offset:5376
	s_waitcnt vmcnt(2) lgkmcnt(2)
	v_mfma_f32_16x16x4_f32 v[76:79], v104, v92, v[76:79]
	v_mfma_f32_16x16x4_f32 v[80:83], v104, v93, v[80:83]
	v_mfma_f32_16x16x4_f32 v[84:87], v104, v94, v[84:87]
	v_mfma_f32_16x16x4_f32 v[88:91], v104, v95, v[88:91]
	global_load_dwordx4 v[92:95], v108, s[0:1]
	v_add_u32_e32 v108, 0x2000, v108
	ds_read_b32 v104, v107 offset:5632
	s_waitcnt vmcnt(2) lgkmcnt(2)
	v_mfma_f32_16x16x4_f32 v[76:79], v105, v96, v[76:79]
	v_mfma_f32_16x16x4_f32 v[80:83], v105, v97, v[80:83]
	v_mfma_f32_16x16x4_f32 v[84:87], v105, v98, v[84:87]
	v_mfma_f32_16x16x4_f32 v[88:91], v105, v99, v[88:91]
	global_load_dwordx4 v[96:99], v108, s[0:1]
	v_add_u32_e32 v108, 0x2000, v108
	ds_read_b32 v105, v107 offset:5888
	s_waitcnt vmcnt(2) lgkmcnt(2)
	v_mfma_f32_16x16x4_f32 v[76:79], v106, v100, v[76:79]
	v_mfma_f32_16x16x4_f32 v[80:83], v106, v101, v[80:83]
	v_mfma_f32_16x16x4_f32 v[84:87], v106, v102, v[84:87]
	v_mfma_f32_16x16x4_f32 v[88:91], v106, v103, v[88:91]
	global_load_dwordx4 v[100:103], v108, s[0:1]
	v_add_u32_e32 v108, 0x2000, v108
	ds_read_b32 v106, v107 offset:6144
	s_waitcnt vmcnt(2) lgkmcnt(2)
	v_mfma_f32_16x16x4_f32 v[76:79], v104, v92, v[76:79]
	v_mfma_f32_16x16x4_f32 v[80:83], v104, v93, v[80:83]
	v_mfma_f32_16x16x4_f32 v[84:87], v104, v94, v[84:87]
	v_mfma_f32_16x16x4_f32 v[88:91], v104, v95, v[88:91]
	global_load_dwordx4 v[92:95], v108, s[0:1]
	v_add_u32_e32 v108, 0x2000, v108
	ds_read_b32 v104, v107 offset:6400
	s_waitcnt vmcnt(2) lgkmcnt(2)
	v_mfma_f32_16x16x4_f32 v[76:79], v105, v96, v[76:79]
	v_mfma_f32_16x16x4_f32 v[80:83], v105, v97, v[80:83]
	v_mfma_f32_16x16x4_f32 v[84:87], v105, v98, v[84:87]
	v_mfma_f32_16x16x4_f32 v[88:91], v105, v99, v[88:91]
	global_load_dwordx4 v[96:99], v108, s[0:1]
	v_add_u32_e32 v108, 0x2000, v108
	ds_read_b32 v105, v107 offset:6656
	s_waitcnt vmcnt(2) lgkmcnt(2)
	v_mfma_f32_16x16x4_f32 v[76:79], v106, v100, v[76:79]
	v_mfma_f32_16x16x4_f32 v[80:83], v106, v101, v[80:83]
	v_mfma_f32_16x16x4_f32 v[84:87], v106, v102, v[84:87]
	v_mfma_f32_16x16x4_f32 v[88:91], v106, v103, v[88:91]
	global_load_dwordx4 v[100:103], v108, s[0:1]
	v_add_u32_e32 v108, 0x2000, v108
	ds_read_b32 v106, v107 offset:6912
	s_waitcnt vmcnt(2) lgkmcnt(2)
	v_mfma_f32_16x16x4_f32 v[76:79], v104, v92, v[76:79]
	v_mfma_f32_16x16x4_f32 v[80:83], v104, v93, v[80:83]
	v_mfma_f32_16x16x4_f32 v[84:87], v104, v94, v[84:87]
	v_mfma_f32_16x16x4_f32 v[88:91], v104, v95, v[88:91]
	global_load_dwordx4 v[92:95], v108, s[0:1]
	v_add_u32_e32 v108, 0x2000, v108
	ds_read_b32 v104, v107 offset:7168
	s_waitcnt vmcnt(2) lgkmcnt(2)
	v_mfma_f32_16x16x4_f32 v[76:79], v105, v96, v[76:79]
	v_mfma_f32_16x16x4_f32 v[80:83], v105, v97, v[80:83]
	v_mfma_f32_16x16x4_f32 v[84:87], v105, v98, v[84:87]
	v_mfma_f32_16x16x4_f32 v[88:91], v105, v99, v[88:91]
	global_load_dwordx4 v[96:99], v108, s[0:1]
	v_add_u32_e32 v108, 0x2000, v108
	ds_read_b32 v105, v107 offset:7424
	s_waitcnt vmcnt(2) lgkmcnt(2)
	v_mfma_f32_16x16x4_f32 v[76:79], v106, v100, v[76:79]
	v_mfma_f32_16x16x4_f32 v[80:83], v106, v101, v[80:83]
	v_mfma_f32_16x16x4_f32 v[84:87], v106, v102, v[84:87]
	v_mfma_f32_16x16x4_f32 v[88:91], v106, v103, v[88:91]
	global_load_dwordx4 v[100:103], v108, s[0:1]
	v_add_u32_e32 v108, 0x2000, v108
	ds_read_b32 v106, v107 offset:7680
	s_waitcnt vmcnt(2) lgkmcnt(2)
	v_mfma_f32_16x16x4_f32 v[76:79], v104, v92, v[76:79]
	v_mfma_f32_16x16x4_f32 v[80:83], v104, v93, v[80:83]
	v_mfma_f32_16x16x4_f32 v[84:87], v104, v94, v[84:87]
	v_mfma_f32_16x16x4_f32 v[88:91], v104, v95, v[88:91]
	global_load_dwordx4 v[92:95], v108, s[0:1]
	v_add_u32_e32 v108, 0x2000, v108
	ds_read_b32 v104, v107 offset:7936
	s_waitcnt vmcnt(2) lgkmcnt(2)
	v_mfma_f32_16x16x4_f32 v[76:79], v105, v96, v[76:79]
	v_mfma_f32_16x16x4_f32 v[80:83], v105, v97, v[80:83]
	v_mfma_f32_16x16x4_f32 v[84:87], v105, v98, v[84:87]
	v_mfma_f32_16x16x4_f32 v[88:91], v105, v99, v[88:91]
	s_waitcnt vmcnt(1) lgkmcnt(1)
	v_mfma_f32_16x16x4_f32 v[76:79], v106, v100, v[76:79]
	v_mfma_f32_16x16x4_f32 v[80:83], v106, v101, v[80:83]
	v_mfma_f32_16x16x4_f32 v[84:87], v106, v102, v[84:87]
	v_mfma_f32_16x16x4_f32 v[88:91], v106, v103, v[88:91]
	s_waitcnt vmcnt(0) lgkmcnt(0)
	v_mfma_f32_16x16x4_f32 v[76:79], v104, v92, v[76:79]
	v_mfma_f32_16x16x4_f32 v[80:83], v104, v93, v[80:83]
	v_mfma_f32_16x16x4_f32 v[84:87], v104, v94, v[84:87]
	v_mfma_f32_16x16x4_f32 v[88:91], v104, v95, v[88:91]
	s_nop 15
	s_nop 3
	ds_write_b32 v109, v76 offset:8192
	ds_write_b32 v109, v77 offset:8448
	ds_write_b32 v109, v78 offset:8704
	ds_write_b32 v109, v79 offset:8960
	ds_write_b32 v109, v80 offset:8196
	ds_write_b32 v109, v81 offset:8452
	ds_write_b32 v109, v82 offset:8708
	ds_write_b32 v109, v83 offset:8964
	ds_write_b32 v109, v84 offset:8200
	ds_write_b32 v109, v85 offset:8456
	ds_write_b32 v109, v86 offset:8712
	ds_write_b32 v109, v87 offset:8968
	ds_write_b32 v109, v88 offset:8204
	ds_write_b32 v109, v89 offset:8460
	ds_write_b32 v109, v90 offset:8716
	ds_write_b32 v109, v91 offset:8972
	s_waitcnt lgkmcnt(0)
	ds_read2st64_b32 v[62:63], v110 offset0:0 offset1:1
	ds_read2st64_b32 v[56:57], v110 offset0:2 offset1:3
	ds_read2st64_b32 v[50:51], v110 offset0:4 offset1:5
	ds_read2st64_b32 v[44:45], v110 offset0:6 offset1:7
	ds_read2st64_b32 v[38:39], v110 offset0:8 offset1:9
	ds_read2st64_b32 v[32:33], v110 offset0:10 offset1:11
	ds_read2st64_b32 v[26:27], v110 offset0:12 offset1:13
	ds_read2st64_b32 v[20:21], v110 offset0:14 offset1:15
	ds_read2st64_b32 v[64:65], v110 offset0:16 offset1:17
	ds_read2st64_b32 v[58:59], v110 offset0:18 offset1:19
	ds_read2st64_b32 v[52:53], v110 offset0:20 offset1:21
	ds_read2st64_b32 v[46:47], v110 offset0:22 offset1:23
	s_waitcnt lgkmcnt(0)
	ds_read2st64_b32 v[40:41], v110 offset0:24 offset1:25
	ds_read2st64_b32 v[34:35], v110 offset0:26 offset1:27
	ds_read2st64_b32 v[28:29], v110 offset0:28 offset1:29
	ds_read2st64_b32 v[22:23], v110 offset0:30 offset1:31
	ds_read2st64_b32 v[66:67], v110 offset0:32 offset1:33
	ds_read2st64_b32 v[60:61], v110 offset0:34 offset1:35
	ds_read2st64_b32 v[54:55], v110 offset0:36 offset1:37
	ds_read2st64_b32 v[48:49], v110 offset0:38 offset1:39
	ds_read2st64_b32 v[42:43], v110 offset0:40 offset1:41
	ds_read2st64_b32 v[36:37], v110 offset0:42 offset1:43
	ds_read2st64_b32 v[30:31], v110 offset0:44 offset1:45
	ds_read2st64_b32 v[24:25], v110 offset0:46 offset1:47
	s_waitcnt lgkmcnt(0)
	s_waitcnt lgkmcnt(0)
	s_ashr_i32 s19, s18, 31
	s_lshl_b64 s[0:1], s[18:19], 10
	v_lshlrev_b32_e32 v78, 1, v164
	v_or_b32_e32 v74, s0, v78
	v_mov_b32_e32 v75, s1
	s_or_b32 s0, s18, 1
	v_cvt_pk_bf16_f32 v17, v62, v1
	v_lshl_add_u64 v[76:77], s[12:13], 0, v[74:75]
	s_ashr_i32 s1, s0, 31
	global_store_short v[76:77], v17, off
	v_cvt_pk_bf16_f32 v17, v64, v1
	v_lshl_add_u64 v[76:77], s[14:15], 0, v[74:75]
	v_lshl_add_u64 v[74:75], s[92:93], 0, v[74:75]
	s_lshl_b64 s[0:1], s[0:1], 9
	global_store_short v[76:77], v17, off
	v_cvt_pk_bf16_f32 v17, v66, v1
	global_store_short v[74:75], v17, off
	v_lshl_add_u64 v[74:75], s[0:1], 0, v[164:165]
	v_cvt_pk_bf16_f32 v17, v63, v1
	v_lshlrev_b64 v[62:63], 1, v[74:75]
	s_or_b32 s0, s18, 2
	v_lshl_add_u64 v[74:75], s[12:13], 0, v[62:63]
	s_ashr_i32 s1, s0, 31
	global_store_short v[74:75], v17, off
	v_cvt_pk_bf16_f32 v17, v65, v1
	v_lshl_add_u64 v[64:65], s[14:15], 0, v[62:63]
	v_lshl_add_u64 v[62:63], s[92:93], 0, v[62:63]
	s_lshl_b64 s[0:1], s[0:1], 10
	global_store_short v[64:65], v17, off
	v_cvt_pk_bf16_f32 v17, v67, v1
	global_store_short v[62:63], v17, off
	v_or_b32_e32 v62, s0, v78
	v_mov_b32_e32 v63, s1
	s_or_b32 s0, s18, 3
	v_cvt_pk_bf16_f32 v17, v56, v1
	v_lshl_add_u64 v[64:65], s[12:13], 0, v[62:63]
	s_ashr_i32 s1, s0, 31
	global_store_short v[64:65], v17, off
	v_cvt_pk_bf16_f32 v17, v58, v1
	v_lshl_add_u64 v[64:65], s[14:15], 0, v[62:63]
	v_lshl_add_u64 v[62:63], s[92:93], 0, v[62:63]
	s_lshl_b64 s[0:1], s[0:1], 9
	global_store_short v[64:65], v17, off
	v_cvt_pk_bf16_f32 v17, v60, v1
	global_store_short v[62:63], v17, off
	v_lshl_add_u64 v[62:63], s[0:1], 0, v[164:165]
	v_cvt_pk_bf16_f32 v17, v57, v1
	v_lshlrev_b64 v[56:57], 1, v[62:63]
	s_or_b32 s0, s18, 4
	v_lshl_add_u64 v[62:63], s[12:13], 0, v[56:57]
	s_ashr_i32 s1, s0, 31
	global_store_short v[62:63], v17, off
	v_cvt_pk_bf16_f32 v17, v59, v1
	v_lshl_add_u64 v[58:59], s[14:15], 0, v[56:57]
	v_lshl_add_u64 v[56:57], s[92:93], 0, v[56:57]
	s_lshl_b64 s[0:1], s[0:1], 10
	global_store_short v[58:59], v17, off
	v_cvt_pk_bf16_f32 v17, v61, v1
	global_store_short v[56:57], v17, off
	v_or_b32_e32 v56, s0, v78
	v_mov_b32_e32 v57, s1
	s_or_b32 s0, s18, 5
	v_cvt_pk_bf16_f32 v17, v50, v1
	v_lshl_add_u64 v[58:59], s[12:13], 0, v[56:57]
	s_ashr_i32 s1, s0, 31
	global_store_short v[58:59], v17, off
	v_cvt_pk_bf16_f32 v17, v52, v1
	v_lshl_add_u64 v[58:59], s[14:15], 0, v[56:57]
	v_lshl_add_u64 v[56:57], s[92:93], 0, v[56:57]
	s_lshl_b64 s[0:1], s[0:1], 9
	global_store_short v[58:59], v17, off
	v_cvt_pk_bf16_f32 v17, v54, v1
	global_store_short v[56:57], v17, off
	v_lshl_add_u64 v[56:57], s[0:1], 0, v[164:165]
	v_cvt_pk_bf16_f32 v17, v51, v1
	v_lshlrev_b64 v[50:51], 1, v[56:57]
	s_or_b32 s0, s18, 6
	v_lshl_add_u64 v[56:57], s[12:13], 0, v[50:51]
	s_ashr_i32 s1, s0, 31
	global_store_short v[56:57], v17, off
	v_cvt_pk_bf16_f32 v17, v53, v1
	v_lshl_add_u64 v[52:53], s[14:15], 0, v[50:51]
	v_lshl_add_u64 v[50:51], s[92:93], 0, v[50:51]
	s_lshl_b64 s[0:1], s[0:1], 10
	global_store_short v[52:53], v17, off
	v_cvt_pk_bf16_f32 v17, v55, v1
	global_store_short v[50:51], v17, off
	v_or_b32_e32 v50, s0, v78
	v_mov_b32_e32 v51, s1
	s_or_b32 s0, s18, 7
	v_cvt_pk_bf16_f32 v17, v44, v1
	v_lshl_add_u64 v[52:53], s[12:13], 0, v[50:51]
	s_ashr_i32 s1, s0, 31
	global_store_short v[52:53], v17, off
	v_cvt_pk_bf16_f32 v17, v46, v1
	v_lshl_add_u64 v[52:53], s[14:15], 0, v[50:51]
	v_lshl_add_u64 v[50:51], s[92:93], 0, v[50:51]
	s_lshl_b64 s[0:1], s[0:1], 9
	global_store_short v[52:53], v17, off
	v_cvt_pk_bf16_f32 v17, v48, v1
	global_store_short v[50:51], v17, off
	v_lshl_add_u64 v[50:51], s[0:1], 0, v[164:165]
	v_cvt_pk_bf16_f32 v17, v45, v1
	v_lshlrev_b64 v[44:45], 1, v[50:51]
	s_or_b32 s0, s18, 8
	v_lshl_add_u64 v[50:51], s[12:13], 0, v[44:45]
	s_ashr_i32 s1, s0, 31
	global_store_short v[50:51], v17, off
	v_cvt_pk_bf16_f32 v17, v47, v1
	v_lshl_add_u64 v[46:47], s[14:15], 0, v[44:45]
	v_lshl_add_u64 v[44:45], s[92:93], 0, v[44:45]
	s_lshl_b64 s[0:1], s[0:1], 10
	global_store_short v[46:47], v17, off
	v_cvt_pk_bf16_f32 v17, v49, v1
	global_store_short v[44:45], v17, off
	v_or_b32_e32 v44, s0, v78
	v_mov_b32_e32 v45, s1
	s_or_b32 s0, s18, 9
	v_cvt_pk_bf16_f32 v17, v38, v1
	v_lshl_add_u64 v[46:47], s[12:13], 0, v[44:45]
	s_ashr_i32 s1, s0, 31
	global_store_short v[46:47], v17, off
	v_cvt_pk_bf16_f32 v17, v40, v1
	v_lshl_add_u64 v[46:47], s[14:15], 0, v[44:45]
	v_lshl_add_u64 v[44:45], s[92:93], 0, v[44:45]
	s_lshl_b64 s[0:1], s[0:1], 9
	global_store_short v[46:47], v17, off
	v_cvt_pk_bf16_f32 v17, v42, v1
	global_store_short v[44:45], v17, off
	v_lshl_add_u64 v[44:45], s[0:1], 0, v[164:165]
	v_cvt_pk_bf16_f32 v17, v39, v1
	v_lshlrev_b64 v[38:39], 1, v[44:45]
	s_or_b32 s0, s18, 10
	v_lshl_add_u64 v[44:45], s[12:13], 0, v[38:39]
	s_ashr_i32 s1, s0, 31
	global_store_short v[44:45], v17, off
	v_cvt_pk_bf16_f32 v17, v41, v1
	v_lshl_add_u64 v[40:41], s[14:15], 0, v[38:39]
	v_lshl_add_u64 v[38:39], s[92:93], 0, v[38:39]
	s_lshl_b64 s[0:1], s[0:1], 10
	global_store_short v[40:41], v17, off
	v_cvt_pk_bf16_f32 v17, v43, v1
	global_store_short v[38:39], v17, off
	v_or_b32_e32 v38, s0, v78
	v_mov_b32_e32 v39, s1
	s_or_b32 s0, s18, 11
	v_cvt_pk_bf16_f32 v17, v32, v1
	v_lshl_add_u64 v[40:41], s[12:13], 0, v[38:39]
	s_ashr_i32 s1, s0, 31
	global_store_short v[40:41], v17, off
	v_cvt_pk_bf16_f32 v17, v34, v1
	v_lshl_add_u64 v[40:41], s[14:15], 0, v[38:39]
	v_lshl_add_u64 v[38:39], s[92:93], 0, v[38:39]
	s_lshl_b64 s[0:1], s[0:1], 9
	global_store_short v[40:41], v17, off
	v_cvt_pk_bf16_f32 v17, v36, v1
	global_store_short v[38:39], v17, off
	v_lshl_add_u64 v[38:39], s[0:1], 0, v[164:165]
	v_cvt_pk_bf16_f32 v17, v33, v1
	v_lshlrev_b64 v[32:33], 1, v[38:39]
	s_or_b32 s0, s18, 12
	v_lshl_add_u64 v[38:39], s[12:13], 0, v[32:33]
	s_ashr_i32 s1, s0, 31
	global_store_short v[38:39], v17, off
	v_cvt_pk_bf16_f32 v17, v35, v1
	v_lshl_add_u64 v[34:35], s[14:15], 0, v[32:33]
	v_lshl_add_u64 v[32:33], s[92:93], 0, v[32:33]
	s_lshl_b64 s[0:1], s[0:1], 10
	global_store_short v[34:35], v17, off
	v_cvt_pk_bf16_f32 v17, v37, v1
	global_store_short v[32:33], v17, off
	v_or_b32_e32 v32, s0, v78
	v_mov_b32_e32 v33, s1
	s_or_b32 s0, s18, 13
	v_cvt_pk_bf16_f32 v17, v26, v1
	v_lshl_add_u64 v[34:35], s[12:13], 0, v[32:33]
	s_ashr_i32 s1, s0, 31
	global_store_short v[34:35], v17, off
	v_cvt_pk_bf16_f32 v17, v28, v1
	v_lshl_add_u64 v[34:35], s[14:15], 0, v[32:33]
	v_lshl_add_u64 v[32:33], s[92:93], 0, v[32:33]
	s_lshl_b64 s[0:1], s[0:1], 9
	global_store_short v[34:35], v17, off
	v_cvt_pk_bf16_f32 v17, v30, v1
	global_store_short v[32:33], v17, off
	v_lshl_add_u64 v[32:33], s[0:1], 0, v[164:165]
	v_cvt_pk_bf16_f32 v17, v27, v1
	v_lshlrev_b64 v[26:27], 1, v[32:33]
	s_or_b32 s0, s18, 14
	v_lshl_add_u64 v[32:33], s[12:13], 0, v[26:27]
	s_ashr_i32 s1, s0, 31
	global_store_short v[32:33], v17, off
	v_cvt_pk_bf16_f32 v17, v29, v1
	v_lshl_add_u64 v[28:29], s[14:15], 0, v[26:27]
	v_lshl_add_u64 v[26:27], s[92:93], 0, v[26:27]
	s_lshl_b64 s[0:1], s[0:1], 10
	global_store_short v[28:29], v17, off
	v_cvt_pk_bf16_f32 v17, v31, v1
	global_store_short v[26:27], v17, off
	v_or_b32_e32 v26, s0, v78
	v_mov_b32_e32 v27, s1
	s_or_b32 s0, s18, 15
	v_cvt_pk_bf16_f32 v17, v20, v1
	v_lshl_add_u64 v[28:29], s[12:13], 0, v[26:27]
	s_ashr_i32 s1, s0, 31
	global_store_short v[28:29], v17, off
	v_cvt_pk_bf16_f32 v17, v22, v1
	v_lshl_add_u64 v[28:29], s[14:15], 0, v[26:27]
	v_lshl_add_u64 v[26:27], s[92:93], 0, v[26:27]
	s_lshl_b64 s[0:1], s[0:1], 9
	global_store_short v[28:29], v17, off
	v_cvt_pk_bf16_f32 v17, v24, v1
	global_store_short v[26:27], v17, off
	v_lshl_add_u64 v[26:27], s[0:1], 0, v[164:165]
	v_cvt_pk_bf16_f32 v17, v21, v1
	v_lshlrev_b64 v[20:21], 1, v[26:27]
	v_lshl_add_u64 v[26:27], s[12:13], 0, v[20:21]
	s_add_i32 s48, s48, s30
	global_store_short v[26:27], v17, off
	v_cvt_pk_bf16_f32 v17, v23, v1
	v_lshl_add_u64 v[22:23], s[14:15], 0, v[20:21]
	v_lshl_add_u64 v[20:21], s[92:93], 0, v[20:21]
	s_cmpk_gt_i32 s48, 0x3ff
	global_store_short v[22:23], v17, off
	v_cvt_pk_bf16_f32 v17, v25, v1
	global_store_short v[20:21], v17, off
	s_barrier
	s_cbranch_scc0 .LBB0_944
